# closing s_barrier of the grid barriers before GEMM phases (and of the first one) moved into the GEMM prologue after the weight-tile DMA issue
# speedup vs baseline: 1.0014x; 1.0014x over previous
; __device__ __forceinline__ unsigned xb_ld(unsigned* p)              { return __hip_atomic_load(p, __ATOMIC_RELAXED, __HIP_MEMORY_SCOPE_AGENT); }
; __device__ __forceinline__ unsigned xb_add(unsigned* p, unsigned v) { return __hip_atomic_fetch_add(p, v, __ATOMIC_RELAXED, __HIP_MEMORY_SCOPE_AGENT); }
; #define XB_SPIN(cond, bar) do { unsigned _sp = 0; while (cond) { __builtin_amdgcn_s_sleep(1); \
;     if ((++_sp & 255u) == 0u) { if (xb_ld(&(bar)[XB_TMO])) break; if (_sp > XB_SPIN_CAP) { atomicAdd(&(bar)[XB_TMO], 1u); break; } } } } while (0)
; __device__ __forceinline__ void xcd_barrier(const XcdBarrier& b) {
;     ...
;             __builtin_amdgcn_fence(__ATOMIC_RELEASE, "agent");
;             asm volatile("s_waitcnt vmcnt(0)" ::: "memory");
;             const unsigned og = xb_add(&bar[XB_TOP], 1u);
;             const unsigned tg = og / nx;
;             if (og + 1u == (tg + 1u) * nx) xb_add(&bar[XB_TOPGEN], 1u);
;             else XB_SPIN(xb_ld(&bar[XB_TOPGEN]) == tg, bar);
;             __builtin_amdgcn_fence(__ATOMIC_ACQUIRE, "agent");
;             xb_add(&bar[XB_XGEN(b.x)], 1u);
;             asm volatile("s_waitcnt vmcnt(0)" ::: "memory");
;         } else {
;             XB_SPIN(xb_ld(&bar[XB_XGEN(b.x)]) == gen, bar);
;             __builtin_amdgcn_fence(__ATOMIC_ACQUIRE, "agent");
;             asm volatile("s_waitcnt vmcnt(0)" ::: "memory");
;         }
;     }
;     __syncthreads();
; template <int PHM, int MIXM>
; __global__ void __launch_bounds__(512, 2) mega(Args Aval) {
;     ...
;     for (int l = 0; l < DEPTH; ++l) {
;         const int pb = 1 + 12 * l;
;         unsigned char* wl = ws + WS_W + (size_t)l * WL_SIZE;
.LBB0_198:
	s_or_b64 exec, exec, s[6:7]
	v_mov_b32_e32 v0, 0x2000
	v_mov_b32_e32 v1, 1
	s_waitcnt vmcnt(0)
	buffer_inv sc1
	global_atomic_add v0, v1, s[4:5] offset:1024
	s_waitcnt vmcnt(0)
.LBB0_199:
	s_or_b64 exec, exec, s[2:3]
	s_waitcnt lgkmcnt(0)
	s_nop 0
.LBB0_200:
	v_readlane_b32 s2, v252, 2
	s_waitcnt lgkmcnt(0)
	s_add_u32 s58, s30, 0x14f90000
	v_readlane_b32 s3, v252, 3
	s_addc_u32 s59, s31, 0
	s_add_u32 s2, s30, 0x10000
	v_writelane_b32 v252, s2, 9
	s_addc_u32 s2, s31, 0
	s_add_u32 s60, s30, 0x18f90000
	s_addc_u32 s61, s31, 0
	s_cmpk_lt_i32 s74, 0xb00
	v_writelane_b32 v252, s2, 10
	s_cselect_b64 s[2:3], -1, 0
	v_writelane_b32 v252, s2, 11
	s_ashr_i32 s57, s74, 31
	s_ashr_i32 s62, s76, 31
	v_writelane_b32 v252, s3, 12
	s_lshr_b32 s2, s57, 29
	s_add_i32 s3, s74, s2
	s_ashr_i32 s2, s3, 3
	s_and_b32 s3, s3, -8
	s_sub_i32 s3, s74, s3
	s_add_u32 s4, s30, 0x2200
	s_addc_u32 s5, s31, 0
	v_writelane_b32 v252, s4, 13
	v_mbcnt_lo_u32_b32 v0, -1, 0
	s_mov_b32 s19, 0
	v_writelane_b32 v252, s5, 14
	s_add_u32 s4, s30, 0x2400
	s_addc_u32 s5, s31, 0
	v_writelane_b32 v252, s4, 15
	v_mov_b32_e32 v177, 0
	v_mov_b32_e32 v236, 0x3727c5ac
	v_writelane_b32 v252, s5, 16
	s_add_u32 s4, s30, 0x2500
	s_addc_u32 s5, s31, 0
	v_writelane_b32 v252, s4, 17
	v_mov_b32_e32 v240, 0x260
	v_mov_b32_e32 v245, 0x40c00000
	v_writelane_b32 v252, s5, 18
	s_add_u32 s4, s30, 0x2600
	s_addc_u32 s5, s31, 0
	v_writelane_b32 v252, s4, 19
	v_mov_b64_e32 v[232:233], 0x200
	v_mov_b64_e32 v[234:235], 0x1ff
	v_writelane_b32 v252, s5, 20
	s_add_u32 s4, s30, 0x2700
	s_addc_u32 s5, s31, 0
	v_writelane_b32 v252, s4, 21
	v_mov_b32_e32 v239, 0xba000000
	v_mov_b32_e32 v242, 0x3a000000
	v_writelane_b32 v252, s5, 22
	s_add_u32 s4, s30, 0x2800
	s_addc_u32 s5, s31, 0
	v_writelane_b32 v252, s4, 23
	v_mov_b32_e32 v241, 0xff800000
	v_mbcnt_hi_u32_b32 v179, -1, v0
	v_writelane_b32 v252, s5, 24
	s_add_u32 s4, s30, 0x2900
	s_addc_u32 s5, s31, 0
	v_writelane_b32 v252, s4, 25
	v_mov_b32_e32 v237, 0x80
	s_mov_b32 s70, 0x80000
	v_writelane_b32 v252, s5, 26
	s_add_u32 s4, s30, 0x2a00
	s_addc_u32 s5, s31, 0
	v_writelane_b32 v252, s4, 27
	s_mov_b32 s71, 0x90000
	s_mov_b32 s72, 0xa0000
	v_writelane_b32 v252, s5, 28
	s_add_u32 s4, s30, 0x2b00
	s_addc_u32 s5, s31, 0
	v_writelane_b32 v252, s4, 29
	s_mov_b32 s73, 0xb0000
	s_movk_i32 s75, 0x1000
	v_writelane_b32 v252, s5, 30
	s_add_u32 s4, s30, 0x2c00
	s_addc_u32 s5, s31, 0
	v_writelane_b32 v252, s4, 31
	s_movk_i32 s35, 0x2200
	s_mov_b32 s28, 0x18f96000
	v_writelane_b32 v252, s5, 32
	s_add_u32 s4, s30, 0x2d00
	s_addc_u32 s5, s31, 0
	v_writelane_b32 v252, s4, 33
	s_mov_b64 s[78:79], 0x80000
	s_mov_b64 s[52:53], 0
	v_writelane_b32 v252, s5, 34
	s_add_u32 s4, s30, 0x2e00
	s_addc_u32 s5, s31, 0
	v_writelane_b32 v252, s4, 35
	s_mov_b64 s[80:81], 0x90000
	s_mov_b64 s[82:83], 0xa0000
	v_writelane_b32 v252, s5, 36
	s_add_u32 s4, s30, 0x2f00
	s_addc_u32 s5, s31, 0
	v_writelane_b32 v252, s4, 37
	s_mov_b64 s[84:85], 0xb0000
	s_mov_b32 s86, 0x3b000000
	v_writelane_b32 v252, s5, 38
	s_add_u32 s4, s30, 0x3000
	s_addc_u32 s5, s31, 0
	v_writelane_b32 v252, s4, 39
	s_mov_b64 s[88:89], 0xb80
	s_mov_b64 s[90:91], 0xd80
	v_writelane_b32 v252, s5, 40
	s_add_u32 s4, s30, 0x3100
	s_addc_u32 s5, s31, 0
	v_writelane_b32 v252, s4, 41
	s_mov_b32 s92, s19
	s_nop 0
	v_writelane_b32 v252, s5, 42
	s_add_u32 s4, s30, 0x3200
	s_addc_u32 s5, s31, 0
	v_writelane_b32 v252, s4, 43
	s_nop 1
	v_writelane_b32 v252, s5, 44
	s_add_u32 s4, s30, 0x3300
	s_addc_u32 s5, s31, 0
	v_writelane_b32 v252, s4, 45
	s_cmp_eq_u32 s68, 15
	s_nop 0
	v_writelane_b32 v252, s5, 46
	s_cselect_b64 s[4:5], -1, 0
	v_writelane_b32 v252, s4, 47
	s_cmp_eq_u32 s68, 14
	s_nop 0
	v_writelane_b32 v252, s5, 48
	s_cselect_b64 s[4:5], -1, 0
	v_writelane_b32 v252, s4, 49
	s_cmp_eq_u32 s68, 13
	s_nop 0
	v_writelane_b32 v252, s5, 50
	s_cselect_b64 s[4:5], -1, 0
	v_writelane_b32 v252, s4, 51
	s_cmp_eq_u32 s68, 12
	s_nop 0
	v_writelane_b32 v252, s5, 52
	s_cselect_b64 s[4:5], -1, 0
	v_writelane_b32 v252, s4, 53
	s_cmp_eq_u32 s68, 11
	s_nop 0
	v_writelane_b32 v252, s5, 54
	s_cselect_b64 s[4:5], -1, 0
	v_writelane_b32 v252, s4, 55
	s_cmp_eq_u32 s68, 10
	s_nop 0
	v_writelane_b32 v252, s5, 56
	s_cselect_b64 s[4:5], -1, 0
	v_writelane_b32 v252, s4, 57
	s_cmp_eq_u32 s68, 9
	s_nop 0
	v_writelane_b32 v252, s5, 58
	s_cselect_b64 s[4:5], -1, 0
	v_writelane_b32 v252, s4, 59
	s_cmp_eq_u32 s68, 8
	s_nop 0
	v_writelane_b32 v252, s5, 60
	s_cselect_b64 s[4:5], -1, 0
	v_writelane_b32 v252, s4, 61
	s_cmp_eq_u32 s68, 7
	s_nop 0
	v_writelane_b32 v252, s5, 62
	s_cselect_b64 s[4:5], -1, 0
	v_writelane_b32 v252, s4, 63
	s_cmp_eq_u32 s68, 6
	s_nop 0
	v_writelane_b32 v253, s5, 0
	s_cselect_b64 s[4:5], -1, 0
	v_writelane_b32 v253, s4, 1
	s_cmp_eq_u32 s68, 5
	s_nop 0
	v_writelane_b32 v253, s5, 2
	s_cselect_b64 s[4:5], -1, 0
	v_writelane_b32 v253, s4, 3
	s_cmp_eq_u32 s68, 4
	s_nop 0
	v_writelane_b32 v253, s5, 4
	s_cselect_b64 s[4:5], -1, 0
	v_writelane_b32 v253, s4, 5
	s_cmp_eq_u32 s68, 3
	s_nop 0
	v_writelane_b32 v253, s5, 6
	s_cselect_b64 s[4:5], -1, 0
	v_writelane_b32 v253, s4, 7
	s_cmp_eq_u32 s68, 2
	s_nop 0
	v_writelane_b32 v253, s5, 8
	s_cselect_b64 s[4:5], -1, 0
	v_writelane_b32 v253, s4, 9
	s_cmp_eq_u32 s68, 1
	s_nop 0
	v_writelane_b32 v253, s5, 10
	s_cselect_b64 s[4:5], -1, 0
	v_writelane_b32 v253, s4, 11
	s_cmp_eq_u32 s68, 0
	s_nop 0
	v_writelane_b32 v253, s5, 12
	s_cselect_b64 s[4:5], -1, 0
	v_writelane_b32 v253, s4, 13
	s_nop 1
	v_writelane_b32 v253, s5, 14
	s_lshl_b32 s4, s68, 8
	s_add_u32 s0, s0, s4
	s_addc_u32 s1, s1, 0
	s_add_u32 s4, s0, 0x1400
	s_addc_u32 s5, s1, 0
	v_writelane_b32 v253, s4, 15
	s_add_u32 s0, s0, 0x2400
	s_addc_u32 s1, s1, 0
;     __device__ bool next(int i, Unit& u) const {
;         const long L = (long)i * G + c; if (L >= nwg) return false;
;         int wgid = (int)L; { const int q = nwg / NXCD, r = nwg % NXCD, xcd = wgid % NXCD, off = wgid / NXCD; wgid = (xcd < r ? xcd * (q + 1) : r * (q + 1) + (xcd - r) * q) + off; }
;         const int nig = WGM * nN, gid = wgid / nig, fm = gid * WGM, gsz = (nM - fm) < WGM ? (nM - fm) : WGM;
;         u.pm = fm + ((wgid % nig) % gsz); u.pn = (wgid % nig) / gsz; return true;
; template <int PHM, int MIXM>
; __global__ void __launch_bounds__(512, 2) mega(Args Aval) {
;     ...
;         for (int rp = 0; rp < ((PROBE_DUP & 512) ? 2 : 1); ++rp) if ((PHM & 16) && IN(pb + 3)) { pg8::Gemm g{XB, (const bf16_t*)(wl + WL_WIN), T, INWP, DM, DM}; pg8::StaticOrder S; S.init(T, INWP, G, bx);
;             pg8::EpiStore E{(bf16_t*)(ws + WS_PROJ), INWP, nullptr, 0, 1.f}; pg8::gemm_phase(ldsl, g, S, E); }
;         if ((PHM & 16) && IN(pb + 3)) { pg8::Gemm g{(const bf16_t*)(ws + WS_PB) + (size_t)l * T * PLE, (const bf16_t*)(wl + WL_WPP), T, DM, PLE, PLE}; pg8::StaticOrder S;
;             if (G == 256) S.init(T, DM, 192, bx >= 64 ? bx - 64 : (1 << 30)); else S.init(T, DM, G, bx);
;             pg8::EpiStore E{(bf16_t*)(ws + WS_PP), DM, nullptr, 0, 1.f}; pg8::gemm_phase(ldsl, g, S, E); }
	v_writelane_b32 v253, s5, 16
	v_writelane_b32 v253, s0, 17
	s_movk_i32 s68, 0x100
	s_nop 0
	v_writelane_b32 v253, s1, 18
	s_add_u32 s0, s30, 0x5400
	s_addc_u32 s1, s31, 0
	v_writelane_b32 v253, s0, 19
	s_nop 1
	v_writelane_b32 v253, s1, 20
	s_add_u32 s0, s30, 0x5500
	s_addc_u32 s1, s31, 0
	s_add_u32 s64, s30, 0x24f90000
	s_addc_u32 s65, s31, 0
	v_writelane_b32 v253, s0, 21
	s_cmpk_lt_i32 s74, 0x200
	s_nop 0
	v_writelane_b32 v253, s1, 22
	s_cselect_b64 s[0:1], -1, 0
	v_writelane_b32 v253, s0, 23
	s_lshl_b32 s14, s74, 3
	s_lshl_b32 s63, s76, 3
	v_writelane_b32 v253, s1, 24
	s_lshl_b32 s0, s3, 6
	s_add_u32 s66, s30, 0x2ecc0000
	s_addc_u32 s67, s31, 0
	s_cmpk_lt_i32 s74, 0x440
	s_cselect_b64 s[4:5], -1, 0
	v_writelane_b32 v253, s4, 25
	s_add_u32 s1, s30, 0x2cf90000
	s_nop 0
	v_writelane_b32 v253, s5, 26
	v_writelane_b32 v253, s1, 27
	s_addc_u32 s1, s31, 0
	v_writelane_b32 v253, s1, 28
	s_sub_i32 s1, s74, 64
	s_cmp_gt_i32 s74, 63
	s_cselect_b32 s1, s1, 2.0
	s_cmpk_eq_i32 s76, 0x100
	s_cselect_b32 s4, s1, s74
	s_cselect_b32 s5, 0xc0, s76
	s_add_u32 s6, s30, 0x28f90000
	s_addc_u32 s7, s31, 0
	v_writelane_b32 v253, s6, 29
	s_cmpk_lt_i32 s4, 0x200
	s_nop 0
	v_writelane_b32 v253, s7, 30
	s_cselect_b64 s[6:7], -1, 0
	v_writelane_b32 v253, s6, 31
	s_ashr_i32 s1, s4, 31
	s_nop 0
	v_writelane_b32 v253, s7, 32
	v_writelane_b32 v253, s1, 33
	s_lshr_b32 s1, s1, 29
	s_add_i32 s1, s4, s1
	s_ashr_i32 s6, s1, 3
	s_and_b32 s1, s1, -8
	s_sub_i32 s7, s4, s1
	s_lshl_b32 s8, s7, 6
	s_ashr_i32 s1, s5, 31
	s_add_u32 s15, s30, 0x18f90800
	v_writelane_b32 v253, s4, 34
	s_addc_u32 s16, s31, 0
	v_writelane_b32 v253, s5, 35
	s_add_u32 s4, s30, 0x22f90000
	v_writelane_b32 v253, s1, 36
	s_addc_u32 s5, s31, 0
	v_writelane_b32 v253, s4, 37
	s_nop 1
	v_writelane_b32 v253, s5, 38
	s_add_u32 s4, s30, 0x2e390000
	s_addc_u32 s5, s31, 0
	v_writelane_b32 v253, s4, 39
	s_nop 1
	v_writelane_b32 v253, s5, 40
	s_add_u32 s4, s30, 0x2e390004
	s_addc_u32 s5, s31, 0
	v_writelane_b32 v253, s4, 41
	s_cmpk_lt_i32 s74, 0x100
	s_nop 0
	v_writelane_b32 v253, s5, 42
	s_cselect_b64 s[4:5], -1, 0
	s_lshl_b32 s1, s3, 5
	s_add_u32 s17, s30, 0x18f90400
	v_writelane_b32 v253, s4, 43
	s_addc_u32 s18, s31, 0
	s_nop 0
	v_writelane_b32 v253, s5, 44
	s_add_u32 s4, s30, 0x21790000
	s_addc_u32 s5, s31, 0
	v_writelane_b32 v253, s4, 45
	s_cmpk_lt_i32 s74, 0xc0
	s_nop 0
	v_writelane_b32 v253, s5, 46
	s_cselect_b64 s[4:5], -1, 0
	v_writelane_b32 v253, s4, 47
	s_cmpk_lt_i32 s74, 0xd00
	s_nop 0
	v_writelane_b32 v253, s5, 48
	s_cselect_b64 s[4:5], -1, 0
	v_writelane_b32 v253, s4, 49
	s_cmp_lt_i32 s3, 0
	s_nop 0
	v_writelane_b32 v253, s5, 50
	s_mul_i32 s4, s3, 0x41
	s_cselect_b32 s9, s4, s0
	s_mul_i32 s0, s3, 33
	s_cselect_b32 s10, s0, s1
	s_movk_i32 s0, 0x161
	s_cselect_b32 s0, s0, 0x160
	s_mul_i32 s4, s3, s0
	s_movk_i32 s0, 0x89
	s_cselect_b32 s11, s0, 0x88
	s_movk_i32 s0, 0x1a1
	s_cselect_b32 s1, 25, 24
	s_cselect_b32 s0, s0, 0x1a0
	s_add_i32 s4, s4, s2
	s_mul_hi_i32 s5, s4, 0x2e8ba2e9
	s_lshr_b32 s12, s5, 31
	s_ashr_i32 s5, s5, 6
	s_add_i32 s5, s5, s12
	s_mul_i32 s12, s5, 0x160
	s_sub_i32 s4, s4, s12
	s_bfe_u32 s12, s4, 0x3001c
	s_add_i32 s12, s4, s12
	s_and_b32 s13, s12, 0xfff8
	s_sub_i32 s4, s4, s13
	s_lshl_b32 s5, s5, 3
	s_sext_i32_i16 s12, s12
	s_sext_i32_i16 s4, s4
	s_add_i32 s20, s5, s4
	s_ashr_i32 s4, s12, 3
	v_writelane_b32 v253, s4, 51
	s_lshr_b32 s4, s12, 3
	s_bfe_i64 s[4:5], s[4:5], 0x100000
	v_writelane_b32 v253, s4, 52
	s_ashr_i32 s21, s20, 31
	s_mul_i32 s1, s3, s1
	v_writelane_b32 v253, s5, 53
	s_mov_b32 s4, s20
	v_writelane_b32 v253, s4, 54
	s_mul_i32 s0, s3, s0
	s_nop 0
	v_writelane_b32 v253, s5, 55
	s_lshl_b64 s[4:5], s[20:21], 20
	s_add_u32 s4, s58, s4
	s_addc_u32 s5, s59, s5
	s_add_u32 s12, s4, 0x80000
	v_writelane_b32 v253, s4, 56
	s_addc_u32 s13, s5, 0
	s_nop 0
	v_writelane_b32 v253, s5, 57
	s_add_i32 s4, s9, s2
	s_ashr_i32 s5, s4, 31
	s_lshr_b32 s5, s5, 26
	s_add_i32 s5, s4, s5
	s_and_b32 s9, s5, 0xffc0
	s_sub_i32 s4, s4, s9
	s_bfe_i32 s9, s4, 0x80000
	s_bfe_u32 s9, s9, 0x3000c
	v_writelane_b32 v253, s12, 58
	s_add_i32 s9, s4, s9
	s_ashr_i32 s5, s5, 6
	v_writelane_b32 v253, s13, 59
	s_and_b32 s12, s9, 0xf8
	s_sub_i32 s4, s4, s12
	s_bfe_i32 s9, s9, 0x80000
	s_lshl_b32 s5, s5, 3
	s_sext_i32_i16 s9, s9
	s_sext_i32_i8 s4, s4
	s_add_i32 s12, s5, s4
	s_ashr_i32 s4, s9, 3
	v_writelane_b32 v253, s4, 60
	s_lshr_b32 s4, s9, 3
	s_bfe_i64 s[4:5], s[4:5], 0x100000
	v_writelane_b32 v253, s4, 61
	s_ashr_i32 s13, s12, 31
	s_nop 0
	v_writelane_b32 v253, s5, 62
	s_mul_i32 s5, s12, 0x2c0000
	s_mul_hi_i32 s4, s12, 0x2c0000
	s_add_u32 s20, s60, s5
	s_addc_u32 s21, s61, s4
	s_mul_i32 s4, s3, s11
	s_add_u32 s22, s20, 0x160000
	v_writelane_b32 v253, s20, 63
	s_addc_u32 s23, s21, 0
	s_add_i32 s4, s4, s2
	s_mul_hi_i32 s5, s4, 0x78787879
	s_lshr_b32 s9, s5, 31
	s_ashr_i32 s5, s5, 6
	s_add_i32 s5, s5, s9
	s_mul_i32 s9, s5, 0x88
	s_sub_i32 s4, s4, s9
	s_bfe_u32 s9, s4, 0x3001c
	s_add_i32 s9, s4, s9
	s_and_b32 s11, s9, 0xfff8
	v_writelane_b32 v254, s21, 0
	s_sub_i32 s4, s4, s11
	v_writelane_b32 v254, s22, 1
	s_lshl_b32 s5, s5, 3
	s_sext_i32_i16 s9, s9
	s_sext_i32_i16 s4, s4
	v_writelane_b32 v254, s23, 2
	s_add_i32 s20, s5, s4
	s_ashr_i32 s4, s9, 3
	v_writelane_b32 v254, s4, 3
	s_lshr_b32 s4, s9, 3
	s_bfe_i64 s[4:5], s[4:5], 0x100000
	v_writelane_b32 v254, s4, 4
	s_ashr_i32 s21, s20, 31
	s_nop 0
	v_writelane_b32 v254, s5, 5
	s_mov_b32 s4, s20
	v_writelane_b32 v254, s4, 6
;     __device__ bool next(int i, Unit& u) const {
;         const long L = (long)i * G + c; if (L >= nwg) return false;
;         int wgid = (int)L; { const int q = nwg / NXCD, r = nwg % NXCD, xcd = wgid % NXCD, off = wgid / NXCD; wgid = (xcd < r ? xcd * (q + 1) : r * (q + 1) + (xcd - r) * q) + off; }
;         const int nig = WGM * nN, gid = wgid / nig, fm = gid * WGM, gsz = (nM - fm) < WGM ? (nM - fm) : WGM;
;         u.pm = fm + ((wgid % nig) % gsz); u.pn = (wgid % nig) / gsz; return true;
; template <int PHM, int MIXM>
; __global__ void __launch_bounds__(512, 2) mega(Args Aval) {
;     ...
;             { pg8::Gemm g{(const bf16_t*)(ws + WS_PROJ) + C_CKV, (const bf16_t*)(wl + WL_WUKV), T, 1024, 256, INWP}; pg8::StaticOrder S; S.init(T, 1024, G, bx);
;               pg8::EpiStore E{(bf16_t*)(ws + WS_KVM), 1024, (const float*)(ws + WS_RSTD) + 1, 2, 1.f}; pg8::gemm_phase(ldsl, g, S, E); }
;             { pg8::Gemm g{(const bf16_t*)(ws + WS_PROJ) + C_CQ, (const bf16_t*)(wl + WL_WUQ), T, 768, 512, INWP}; pg8::StaticOrder S; S.init(T, 768, G, bx);
;               pg8::EpiStore E{(bf16_t*)(ws + WS_QM), 768, (const float*)(ws + WS_RSTD), 2, 1.f}; pg8::gemm_phase(ldsl, g, S, E); }
	s_nop 1
	v_writelane_b32 v254, s5, 7
	s_lshl_b64 s[4:5], s[20:21], 20
	s_add_u32 s4, s58, s4
	s_addc_u32 s5, s59, s5
	s_add_u32 s20, s4, 0x80000
	v_writelane_b32 v254, s4, 8
	s_addc_u32 s21, s5, 0
	s_cmp_lt_i32 s7, 0
	s_mulk_i32 s7, 0x41
	v_writelane_b32 v254, s5, 9
	s_cselect_b32 s4, s7, s8
	s_add_i32 s4, s4, s6
	s_ashr_i32 s5, s4, 31
	s_lshr_b32 s5, s5, 26
	s_add_i32 s5, s4, s5
	s_and_b32 s6, s5, 0xffc0
	s_sub_i32 s4, s4, s6
	s_bfe_i32 s6, s4, 0x80000
	s_bfe_u32 s6, s6, 0x3000c
	s_add_i32 s6, s4, s6
	s_and_b32 s7, s6, 0xf8
	s_sub_i32 s4, s4, s7
	s_add_i32 s7, s10, s2
	s_ashr_i32 s8, s7, 31
	s_lshr_b32 s8, s8, 27
	s_add_i32 s8, s7, s8
	s_and_b32 s9, s8, 0xffe0
	s_sub_i32 s7, s7, s9
	s_bfe_i32 s9, s7, 0x80000
	s_bfe_u32 s9, s9, 0x3000c
	s_add_i32 s9, s7, s9
	s_ashr_i32 s5, s5, 6
	s_bfe_i32 s6, s6, 0x80000
	v_writelane_b32 v254, s20, 10
	s_and_b32 s10, s9, 0xf8
	s_lshl_b32 s5, s5, 3
	s_sext_i32_i16 s6, s6
	s_sext_i32_i8 s4, s4
	v_writelane_b32 v254, s21, 11
	s_sub_i32 s7, s7, s10
	s_add_i32 s10, s5, s4
	s_ashr_i32 s4, s6, 3
	v_writelane_b32 v254, s4, 12
	s_lshr_b32 s4, s6, 3
	s_bfe_i64 s[4:5], s[4:5], 0x100000
	v_writelane_b32 v254, s4, 13
	s_ashr_i32 s8, s8, 5
	s_lshl_b32 s8, s8, 3
	v_writelane_b32 v254, s5, 14
	s_bfe_i32 s4, s9, 0x80000
	s_sext_i32_i16 s4, s4
	s_ashr_i32 s5, s4, 3
	s_lshr_b32 s4, s4, 3
	v_writelane_b32 v254, s5, 15
	s_bfe_i64 s[4:5], s[4:5], 0x100000
	s_sext_i32_i8 s7, s7
	v_writelane_b32 v254, s4, 16
	s_add_i32 s7, s8, s7
	s_mov_b32 s6, s10
	v_writelane_b32 v254, s5, 17
	v_writelane_b32 v254, s7, 18
	s_ashr_i32 s11, s10, 31
	s_mul_hi_i32 s4, s7, 0x220000
	s_mul_i32 s5, s7, 0x220000
	v_writelane_b32 v254, s6, 19
	s_nop 1
	v_writelane_b32 v254, s7, 20
	s_lshl_b64 s[6:7], s[10:11], 17
	v_writelane_b32 v254, s6, 21
	s_nop 1
	v_writelane_b32 v254, s7, 22
	v_writelane_b32 v254, s15, 23
	s_add_u32 s6, s15, s5
	v_writelane_b32 v254, s16, 24
	s_addc_u32 s7, s16, s4
	s_add_u32 s4, s6, 0x110000
	v_writelane_b32 v254, s6, 25
	s_addc_u32 s5, s7, 0
	s_add_i32 s1, s1, s2
	v_writelane_b32 v254, s7, 26
	v_writelane_b32 v254, s4, 27
	s_mov_b32 s16, 0x3fb504f3
	s_nop 0
	v_writelane_b32 v254, s5, 28
	s_mul_hi_i32 s4, s1, 0x2aaaaaab
	s_lshr_b32 s5, s4, 31
	s_ashr_i32 s4, s4, 2
	s_add_i32 s4, s4, s5
	s_mul_i32 s5, s4, 24
	s_sub_i32 s1, s1, s5
	s_bfe_i32 s5, s1, 0x80000
	s_bfe_u32 s5, s5, 0x3000c
	s_add_i32 s5, s1, s5
	s_and_b32 s6, s5, 0xf8
	s_sub_i32 s1, s1, s6
	s_lshl_b32 s4, s4, 3
	s_sext_i32_i8 s1, s1
	s_add_i32 s6, s4, s1
	s_bfe_i32 s1, s5, 0x80000
	s_sext_i32_i16 s1, s1
	s_ashr_i32 s4, s1, 3
	v_writelane_b32 v254, s4, 29
	s_lshr_b32 s4, s1, 3
	s_bfe_i64 s[4:5], s[4:5], 0x100000
	v_writelane_b32 v254, s4, 30
	s_mul_hi_i32 s1, s6, 0x220000
	s_nop 0
	v_writelane_b32 v254, s5, 31
	v_writelane_b32 v254, s6, 32
	s_mul_i32 s4, s6, 0x220000
	v_writelane_b32 v254, s17, 33
	s_add_u32 s4, s17, s4
	v_writelane_b32 v254, s18, 34
	s_addc_u32 s5, s18, s1
	s_add_u32 s6, s4, 0x110000
	v_writelane_b32 v254, s4, 35
	s_addc_u32 s7, s5, 0
	s_nop 0
	v_writelane_b32 v254, s5, 36
	v_writelane_b32 v254, s6, 37
	s_mov_b32 s4, s12
	s_nop 0
	v_writelane_b32 v254, s7, 38
	v_writelane_b32 v254, s4, 39
	s_nop 1
	v_writelane_b32 v254, s5, 40
	s_lshl_b64 s[4:5], s[12:13], 20
	s_add_u32 s4, s64, s4
	s_addc_u32 s5, s65, s5
	s_add_u32 s6, s4, 0x80000
	v_writelane_b32 v254, s4, 41
	s_addc_u32 s7, s5, 0
	s_add_i32 s0, s0, s2
	s_mul_hi_i32 s1, s0, 0x4ec4ec4f
	s_lshr_b32 s2, s1, 31
	s_ashr_i32 s1, s1, 7
	s_add_i32 s1, s1, s2
	s_mul_i32 s2, s1, 0x1a0
	s_sub_i32 s0, s0, s2
	s_bfe_u32 s2, s0, 0x3001c
	s_add_i32 s2, s0, s2
	s_and_b32 s3, s2, 0xfff8
	v_writelane_b32 v254, s5, 42
	s_sub_i32 s0, s0, s3
	v_writelane_b32 v254, s6, 43
	s_lshl_b32 s1, s1, 3
	s_sext_i32_i16 s2, s2
	s_sext_i32_i16 s0, s0
	v_writelane_b32 v254, s7, 44
	s_add_i32 s4, s1, s0
	s_ashr_i32 s0, s2, 3
	v_writelane_b32 v254, s0, 45
	s_lshr_b32 s0, s2, 3
	s_bfe_i64 s[0:1], s[0:1], 0x100000
	v_writelane_b32 v254, s0, 46
	s_ashr_i32 s5, s4, 31
	s_nop 0
	v_writelane_b32 v254, s1, 47
	s_mov_b32 s0, s4
	v_writelane_b32 v254, s0, 48
	s_nop 1
	v_writelane_b32 v254, s1, 49
	s_lshl_b64 s[0:1], s[4:5], 20
	s_add_u32 s2, s58, s0
	s_mul_i32 s0, s33, s77
	s_mul_i32 s0, s0, s76
	s_addc_u32 s3, s59, s1
	v_writelane_b32 v254, s0, 50
	s_add_u32 s0, s2, 0x80000
	v_writelane_b32 v254, s2, 51
	s_addc_u32 s1, s3, 0
	s_lshl_b32 s69, s76, 4
	v_writelane_b32 v254, s3, 52
	s_mov_b32 s2, s76
	v_writelane_b32 v255, s2, 0
	v_writelane_b32 v254, s0, 53
	s_mov_b32 s77, 0xf800000
	v_writelane_b32 v255, s3, 1
	v_writelane_b32 v255, s58, 2
	v_writelane_b32 v254, s1, 54
	s_xor_b32 s0, s14, 31
	v_writelane_b32 v255, s59, 3
	v_writelane_b32 v255, s60, 4
	v_writelane_b32 v254, s14, 55
	s_add_i32 s0, s0, s63
	v_writelane_b32 v255, s61, 5
	v_writelane_b32 v254, s0, 56
	s_lshl_b32 s0, s74, 4
	v_writelane_b32 v255, s57, 6
	v_writelane_b32 v254, s0, 57
	s_add_i32 s0, 16, 0x20600
	v_writelane_b32 v255, s62, 7
	v_writelane_b32 v254, s0, 58
	v_cmp_eq_u32_e64 s[0:1], 0, v238
	v_writelane_b32 v255, s64, 8
	s_mov_b32 s33, 0x18f94000
	v_writelane_b32 v254, s0, 59
	v_writelane_b32 v255, s65, 9
	v_writelane_b32 v255, s63, 10
	v_writelane_b32 v254, s1, 60
	s_mov_b64 s[0:1], -1
	v_writelane_b32 v254, s0, 61
	v_writelane_b32 v255, s66, 11
	s_nop 0
	v_writelane_b32 v254, s1, 62
	v_writelane_b32 v255, s67, 12
	s_mov_b64 s[0:1], 0x80
	v_writelane_b32 v254, s74, 63
	v_writelane_b32 v255, s69, 13
	s_branch .LBB0_204
